# attention unit prologue: K/V + k-gain loads, the 3 bias-table loads and the sink + first-chunk q loads all issued before the K normalisation (one global round trip per unit instead of three), counted
# baseline (speedup 1.0000x reference)
; __device__ __forceinline__ void attn_phase(int wave_s, LAS unsigned char* lds, const bf16* QKV, bf16* O, const float* qg, const float* kg, const float* sinks, const float* bt) {
;     ...
;         const long rowbase = (long)b * SEQ + (long)(nb - 1) * 128;
; #pragma unroll
;         for (int i = 0; i < 4; ++i) { int tq = tid; asm volatile("" : "+v"(tq)); const int p = tq + NTHR * i, jrow = p >> 3, ch = p & 7; const bool ok = (nb > 0) || (jrow >= 128);
;             v4u kw = (v4u){0u, 0u, 0u, 0u}, vw = (v4u){0u, 0u, 0u, 0u};
;             if (ok) { const bf16* src = QKV + (size_t)(rowbase + jrow) * NQKV + NH * HD + kvh * HD + ch * 8; kw = *(const v4u*)src; vw = *(const v4u*)(src + NKV * HD); }
;             float kf[8] = {bflo(kw.x), bfhi(kw.x), bflo(kw.y), bfhi(kw.y), bflo(kw.z), bfhi(kw.z), bflo(kw.w), bfhi(kw.w)};
;             float s = 0.f;
; #pragma unroll
;             for (int e = 0; e < 8; ++e) s += kf[e] * kf[e];
;             s = sum8(s);
;             const float rs = __builtin_amdgcn_rsqf(s * (1.0f / 64.0f) + EPS);
;             const f32x4 g0 = *(const f32x4*)(kg + ch * 8), g1 = *(const f32x4*)(kg + ch * 8 + 4);
;             v4u ko; ko.x = pk2(kf[0] * rs * g0.x, kf[1] * rs * g0.y); ko.y = pk2(kf[2] * rs * g0.z, kf[3] * rs * g0.w); ko.z = pk2(kf[4] * rs * g1.x, kf[5] * rs * g1.y); ko.w = pk2(kf[6] * rs * g1.z, kf[7] * rs * g1.w);
;             *(LAS v4u*)(Ks + jrow * KS_STRIDE + ch * 8) = ko;
;             LAS bf16* vd = Vt + (ch * 8) * VT_STRIDE + jrow;
;             vd[0 * VT_STRIDE] = (bf16)(vw.x & 0xffffu); vd[1 * VT_STRIDE] = (bf16)(vw.x >> 16); vd[2 * VT_STRIDE] = (bf16)(vw.y & 0xffffu); vd[3 * VT_STRIDE] = (bf16)(vw.y >> 16);
;             vd[4 * VT_STRIDE] = (bf16)(vw.z & 0xffffu); vd[5 * VT_STRIDE] = (bf16)(vw.z >> 16); vd[6 * VT_STRIDE] = (bf16)(vw.w & 0xffffu); vd[7 * VT_STRIDE] = (bf16)(vw.w >> 16); }
;         for (int e = tid; e < 8 * 192; e += NTHR) { const int hh = e / 192, dist = e % 192 - 32; Bs[e] = (dist >= 0 && dist < 128) ? bt[(kvh * 8 + hh) * 128 + dist] - shift * LOG2E : -1e30f; }
;         __syncthreads();
;         const int h = kvh * 8 + wid; const float sink2 = (sinks[h] - shift) * LOG2E;
;         const LAS float* Bh = Bs + wid * 192 + (r32 - 4 * hi);
;         LAS float* wsf = (LAS float*)(lds + ALDS_END) + wid * 32;
;         const bf16* Qb = QKV + ((size_t)b * SEQ + nb * 128 + r32) * NQKV + h * HD + hi * 8;
.LBB0_476:
	s_bfe_u32 s30, s35, 0x60002
	v_mov_b32_e32 v1, v142
	s_barrier
	v_add_co_u32_e64 v2, s[88:89], s30, -1
	s_xor_b64 s[10:11], s[88:89], -1
	v_ashrrev_i32_e32 v12, 3, v142
	v_and_b32_e32 v1, 7, v142
	s_ashr_i32 s6, s35, 8
	s_ashr_i32 s7, s6, 31
	v_ashrrev_i32_e32 v3, 31, v2
	s_and_b32 s31, s35, 3
	s_lshl_b64 s[8:9], s[6:7], 13
	v_lshlrev_b64 v[2:3], 7, v[2:3]
	v_lshl_add_u64 v[10:11], v[2:3], 0, s[8:9]
	s_lshl_b32 s12, s31, 6
	s_lshl_b32 s50, s12, 1
	s_and_b32 s36, s34, 3
	v_lshlrev_b32_e32 v14, 3, v1
	v_mov_b32_e32 v15, v0
	v_lshl_add_u64 v[20:21], v[14:15], 2, s[28:29]
	global_load_dwordx4 v[16:19], v[20:21], off
	s_nop 0
	global_load_dwordx4 v[20:23], v[20:21], off offset:16
	v_ashrrev_i32_e32 v13, 31, v12
	v_lshl_add_u64 v[2:3], v[10:11], 0, v[12:13]
	v_mov_b64_e32 v[4:5], s[26:27]
	v_mad_u64_u32 v[4:5], s[40:41], v2, s70, v[4:5]
	v_mad_i32_i24 v5, v3, s70, v5
	v_lshl_add_u64 v[2:3], v[4:5], 0, s[50:51]
	v_lshlrev_b32_e32 v4, 4, v1
	v_mov_b32_e32 v5, v0
	v_lshl_add_u64 v[2:3], v[2:3], 0, v[4:5]
	v_lshl_add_u64 v[76:77], v[2:3], 0, s[86:87]
	v_add_co_u32_e32 v68, vcc, 0x1000, v2
	s_lshl_b32 s2, s70, 6
	s_mov_b32 s3, 0
	v_addc_co_u32_e32 v69, vcc, 0, v3, vcc
	v_lshl_add_u64 v[70:71], v[68:69], 0, s[2:3]
	v_lshl_add_u64 v[78:79], v[76:77], 0, s[2:3]
	v_lshl_add_u64 v[72:73], v[70:71], 0, s[2:3]
	v_lshl_add_u64 v[80:81], v[78:79], 0, s[2:3]
	v_lshl_add_u64 v[74:75], v[72:73], 0, s[2:3]
	v_lshl_add_u64 v[82:83], v[80:81], 0, s[2:3]
	v_add_u32_e32 v24, 64, v12
	v_add_u32_e32 v25, 0x80, v12
	v_add_u32_e32 v26, 0xc0, v12
	v_mov_b64_e32 v[36:37], 0
	v_mov_b64_e32 v[38:39], 0
	v_mov_b64_e32 v[40:41], 0
	v_mov_b64_e32 v[42:43], 0
	v_mov_b64_e32 v[44:45], 0
	v_mov_b64_e32 v[46:47], 0
	v_mov_b64_e32 v[48:49], 0
	v_mov_b64_e32 v[50:51], 0
	v_mov_b64_e32 v[52:53], 0
	v_mov_b64_e32 v[54:55], 0
	v_mov_b64_e32 v[56:57], 0
	v_mov_b64_e32 v[58:59], 0
	v_mov_b64_e32 v[60:61], 0
	v_mov_b64_e32 v[62:63], 0
	v_mov_b64_e32 v[64:65], 0
	v_mov_b64_e32 v[66:67], 0
	v_mul_lo_u32 v32, v12, s67
	v_lshlrev_b32_e32 v33, 1, v14
	v_lshlrev_b32_e32 v34, 1, v12
	v_mul_u32_u24_e32 v35, 0x1040, v1
	v_add3_u32 v31, 0, v32, v33
	v_add3_u32 v35, 0, v35, v34
	s_mov_b64 s[84:85], exec
	v_cmp_gt_i32_e32 vcc, s66, v12
	s_and_b64 s[40:41], s[10:11], vcc
	s_andn2_b64 exec, s[84:85], s[40:41]
	global_load_dwordx4 v[36:39], v[68:69], off
	global_load_dwordx4 v[52:55], v[76:77], off offset:512
	s_mov_b64 exec, s[84:85]
	v_cmp_gt_i32_e32 vcc, s66, v24
	s_and_b64 s[40:41], s[10:11], vcc
	s_andn2_b64 exec, s[84:85], s[40:41]
	global_load_dwordx4 v[40:43], v[70:71], off
	global_load_dwordx4 v[56:59], v[78:79], off offset:512
	s_mov_b64 exec, s[84:85]
	v_cmp_gt_i32_e32 vcc, s66, v25
	s_and_b64 s[40:41], s[10:11], vcc
	s_andn2_b64 exec, s[84:85], s[40:41]
	global_load_dwordx4 v[44:47], v[72:73], off
	global_load_dwordx4 v[60:63], v[80:81], off offset:512
	s_mov_b64 exec, s[84:85]
	v_cmp_gt_i32_e32 vcc, s66, v26
	s_and_b64 s[40:41], s[10:11], vcc
	s_andn2_b64 exec, s[84:85], s[40:41]
	global_load_dwordx4 v[48:51], v[74:75], off
	global_load_dwordx4 v[64:67], v[82:83], off offset:512
	s_mov_b64 exec, s[84:85]
	s_lshl_b32 s10, s36, 10
	s_sub_i32 s37, s10, 32
	s_mov_b32 s12, 0x2aaaaaab
	s_movk_i32 s13, 0xff40
	s_movk_i32 s40, 0xffe0
	s_add_i32 s10, 0, 0x11200
	v_lshl_add_u32 v112, v142, 2, s10
	v_add_u32_e32 v113, 0x200, v142
	v_add_u32_e32 v114, 0x400, v142
	v_mul_hi_i32 v115, v142, s12
	v_mul_hi_i32 v116, v113, s12
	v_mul_hi_i32 v117, v114, s12
	v_lshrrev_b32_e32 v118, 31, v115
	v_lshrrev_b32_e32 v119, 31, v116
	v_lshrrev_b32_e32 v120, 31, v117
	v_ashrrev_i32_e32 v115, 5, v115
	v_ashrrev_i32_e32 v116, 5, v116
	v_ashrrev_i32_e32 v117, 5, v117
	v_add_u32_e32 v115, v115, v118
	v_add_u32_e32 v116, v116, v119
	v_add_u32_e32 v117, v117, v120
	v_mul_lo_u32 v118, v115, s13
	v_mul_lo_u32 v119, v116, s13
	v_mul_lo_u32 v120, v117, s13
	v_add3_u32 v118, v142, v118, s40
	v_add3_u32 v119, v113, v119, s40
	v_add3_u32 v120, v114, v120, s40
	v_add_u32_e32 v122, s37, v142
	v_add_u32_e32 v124, s37, v113
	v_add_u32_e32 v126, s37, v114
	v_lshlrev_b32_e32 v115, 6, v115
	v_lshlrev_b32_e32 v116, 6, v116
	v_lshlrev_b32_e32 v117, 6, v117
	v_sub_u32_e32 v122, v122, v115
	v_sub_u32_e32 v124, v124, v116
	v_sub_u32_e32 v126, v126, v117
	v_ashrrev_i32_e32 v123, 31, v122
	v_ashrrev_i32_e32 v125, 31, v124
	v_ashrrev_i32_e32 v127, 31, v126
	v_lshl_add_u64 v[122:123], v[122:123], 2, s[20:21]
	v_lshl_add_u64 v[124:125], v[124:125], 2, s[20:21]
	v_lshl_add_u64 v[126:127], v[126:127], 2, s[20:21]
	v_cmp_gt_u32_e64 s[40:41], s66, v118
	v_cmp_gt_u32_e64 s[84:85], s66, v119
	v_cmp_gt_u32_e64 s[90:91], s66, v120
	s_and_b64 s[40:41], s[40:41], s[14:15]
	s_and_b64 s[84:85], s[84:85], s[14:15]
	s_and_b64 s[90:91], s[90:91], s[14:15]
	s_mov_b64 s[94:95], exec
	s_and_b64 exec, s[94:95], s[40:41]
	global_load_dword v92, v[122:123], off
	s_and_b64 exec, s[94:95], s[84:85]
	global_load_dword v93, v[124:125], off
	s_and_b64 exec, s[94:95], s[90:91]
	global_load_dword v94, v[126:127], off
	s_mov_b64 exec, s[94:95]
	s_lshr_b32 s2, s35, 2
	s_and_b32 s10, s2, 63
	s_lshl_b32 s37, s10, 7
	s_lshl_b32 s2, s36, 9
	s_lshl_b32 s36, s10, 19
	s_lshl_b32 s10, s31, 3
	s_add_i32 s2, s23, s2
	s_add_i32 s10, s10, s16
	s_ashr_i32 s3, s2, 31
	s_ashr_i32 s11, s10, 31
	s_lshl_b64 s[2:3], s[2:3], 1
	s_lshl_b64 s[12:13], s[10:11], 2
	s_add_u32 s12, s17, s12
	s_addc_u32 s13, s22, s13
	s_lshl_b32 s11, s30, 7
	s_or_b32 s11, s8, s11
	v_or_b32_e32 v4, s11, v128
	v_mov_b64_e32 v[2:3], s[26:27]
	global_load_dword v1, v0, s[12:13]
	v_mad_u64_u32 v[2:3], s[12:13], v4, s70, v[2:3]
	v_mov_b32_e32 v4, 0x1400
	s_lshl_b32 s10, s10, 6
	v_mad_i32_i24 v3, s9, v4, v3
	s_ashr_i32 s11, s10, 31
	v_lshl_add_u64 v[2:3], s[10:11], 1, v[2:3]
	v_mov_b32_e32 v137, v0
	v_lshl_add_u64 v[2:3], v[2:3], 0, v[136:137]
	global_load_dwordx4 v[96:99], v[2:3], off
	global_load_dwordx4 v[100:103], v[2:3], off offset:32
	global_load_dwordx4 v[104:107], v[2:3], off offset:64
	global_load_dwordx4 v[108:111], v[2:3], off offset:96
	s_lshl_b32 s12, s67, 6
	s_waitcnt vmcnt(15)
; __device__ __forceinline__ float sum8(float s) { s += DPP_MOVF(s, 0xB1); s += DPP_MOVF(s, 0x4E); s += DPP_MOVF(s, 0x141); return s; }
; #define LAS __attribute__((address_space(3)))
; __device__ __forceinline__ unsigned pk2(float lo, float hi) { f32x2_t v = {lo, hi}; bf16x2_t b = __builtin_convertvector(v, bf16x2_t); return __builtin_bit_cast(unsigned, b); }
; __device__ __forceinline__ void attn_phase(int wave_s, LAS unsigned char* lds, const bf16* QKV, bf16* O, const float* qg, const float* kg, const float* sinks, const float* bt) {
;     ...
;         for (int i = 0; i < 4; ++i) { int tq = tid; asm volatile("" : "+v"(tq)); const int p = tq + NTHR * i, jrow = p >> 3, ch = p & 7; const bool ok = (nb > 0) || (jrow >= 128);
;             v4u kw = (v4u){0u, 0u, 0u, 0u}, vw = (v4u){0u, 0u, 0u, 0u};
;             if (ok) { const bf16* src = QKV + (size_t)(rowbase + jrow) * NQKV + NH * HD + kvh * HD + ch * 8; kw = *(const v4u*)src; vw = *(const v4u*)(src + NKV * HD); }
;             float kf[8] = {bflo(kw.x), bfhi(kw.x), bflo(kw.y), bfhi(kw.y), bflo(kw.z), bfhi(kw.z), bflo(kw.w), bfhi(kw.w)};
;             float s = 0.f;
; #pragma unroll
;             for (int e = 0; e < 8; ++e) s += kf[e] * kf[e];
;             s = sum8(s);
;             const float rs = __builtin_amdgcn_rsqf(s * (1.0f / 64.0f) + EPS);
;             const f32x4 g0 = *(const f32x4*)(kg + ch * 8), g1 = *(const f32x4*)(kg + ch * 8 + 4);
;             v4u ko; ko.x = pk2(kf[0] * rs * g0.x, kf[1] * rs * g0.y); ko.y = pk2(kf[2] * rs * g0.z, kf[3] * rs * g0.w); ko.z = pk2(kf[4] * rs * g1.x, kf[5] * rs * g1.y); ko.w = pk2(kf[6] * rs * g1.z, kf[7] * rs * g1.w);
;             *(LAS v4u*)(Ks + jrow * KS_STRIDE + ch * 8) = ko;
;             LAS bf16* vd = Vt + (ch * 8) * VT_STRIDE + jrow;
;             vd[0 * VT_STRIDE] = (bf16)(vw.x & 0xffffu); vd[1 * VT_STRIDE] = (bf16)(vw.x >> 16); vd[2 * VT_STRIDE] = (bf16)(vw.y & 0xffffu); vd[3 * VT_STRIDE] = (bf16)(vw.y >> 16);
;             vd[4 * VT_STRIDE] = (bf16)(vw.z & 0xffffu); vd[5 * VT_STRIDE] = (bf16)(vw.z >> 16); vd[6 * VT_STRIDE] = (bf16)(vw.w & 0xffffu); vd[7 * VT_STRIDE] = (bf16)(vw.w >> 16); }
	v_lshlrev_b32_e32 v28, 16, v36
	v_and_b32_e32 v29, 0xffff0000, v36
	v_lshlrev_b32_e32 v24, 16, v39
	v_and_b32_e32 v25, 0xffff0000, v39
	v_lshlrev_b32_e32 v26, 16, v38
	v_and_b32_e32 v27, 0xffff0000, v38
	v_lshlrev_b32_e32 v8, 16, v37
	v_and_b32_e32 v9, 0xffff0000, v37
	v_pk_mul_f32 v[90:91], v[28:29], v[28:29]
	v_pk_mul_f32 v[84:85], v[8:9], v[8:9]
	v_add_f32_e32 v90, v90, v91
	v_add_f32_e32 v84, v84, v90
	v_pk_mul_f32 v[86:87], v[26:27], v[26:27]
	v_add_f32_e32 v84, v85, v84
	v_add_f32_e32 v86, v86, v84
	v_pk_mul_f32 v[6:7], v[24:25], v[24:25]
	v_add_f32_e32 v86, v87, v86
	v_add_f32_e32 v6, v6, v86
	v_add_f32_e32 v6, v7, v6
	s_nop 1
	v_add_f32_dpp v6, v6, v6 quad_perm:[1,0,3,2] row_mask:0xf bank_mask:0xf bound_ctrl:1
	s_nop 1
	v_add_f32_dpp v6, v6, v6 quad_perm:[2,3,0,1] row_mask:0xf bank_mask:0xf bound_ctrl:1
	s_nop 1
	v_add_f32_dpp v6, v6, v6 row_half_mirror row_mask:0xf bank_mask:0xf bound_ctrl:1
	v_fmamk_f32 v6, v6, 0x3c800000, v250
	v_rsq_f32_e32 v6, v6
	s_nop 0
	v_pk_mul_f32 v[84:85], v[6:7], v[28:29] op_sel_hi:[0,1]
	v_pk_mul_f32 v[8:9], v[6:7], v[8:9] op_sel_hi:[0,1]
	v_pk_mul_f32 v[86:87], v[6:7], v[26:27] op_sel_hi:[0,1]
	v_pk_mul_f32 v[6:7], v[6:7], v[24:25] op_sel_hi:[0,1]
	v_pk_mul_f32 v[84:85], v[16:17], v[84:85]
	v_pk_mul_f32 v[8:9], v[18:19], v[8:9]
	v_pk_mul_f32 v[86:87], v[20:21], v[86:87]
	v_pk_mul_f32 v[88:89], v[22:23], v[6:7]
	v_cvt_pk_bf16_f32 v6, v84, v85
	v_cvt_pk_bf16_f32 v7, v8, v9
	v_cvt_pk_bf16_f32 v8, v86, v87
	v_cvt_pk_bf16_f32 v9, v88, v89
	ds_write_b128 v31, v[6:9]
	v_add_u32_e32 v31, s12, v31
	s_waitcnt vmcnt(14)
	ds_write_b16 v35, v52 offset:36864
	ds_write_b16_d16_hi v35, v52 offset:37384
	ds_write_b16 v35, v53 offset:37904
	ds_write_b16_d16_hi v35, v53 offset:38424
	ds_write_b16 v35, v54 offset:38944
	ds_write_b16_d16_hi v35, v54 offset:39464
	ds_write_b16 v35, v55 offset:39984
	ds_write_b16_d16_hi v35, v55 offset:40504
	s_waitcnt vmcnt(13)
	v_lshlrev_b32_e32 v28, 16, v40
	v_and_b32_e32 v29, 0xffff0000, v40
	v_lshlrev_b32_e32 v24, 16, v43
	v_and_b32_e32 v25, 0xffff0000, v43
	v_lshlrev_b32_e32 v26, 16, v42
	v_and_b32_e32 v27, 0xffff0000, v42
	v_lshlrev_b32_e32 v8, 16, v41
	v_and_b32_e32 v9, 0xffff0000, v41
	v_pk_mul_f32 v[90:91], v[28:29], v[28:29]
	v_pk_mul_f32 v[84:85], v[8:9], v[8:9]
	v_add_f32_e32 v90, v90, v91
	v_add_f32_e32 v84, v84, v90
	v_pk_mul_f32 v[86:87], v[26:27], v[26:27]
	v_add_f32_e32 v84, v85, v84
	v_add_f32_e32 v86, v86, v84
	v_pk_mul_f32 v[6:7], v[24:25], v[24:25]
	v_add_f32_e32 v86, v87, v86
	v_add_f32_e32 v6, v6, v86
	v_add_f32_e32 v6, v7, v6
	s_nop 1
	v_add_f32_dpp v6, v6, v6 quad_perm:[1,0,3,2] row_mask:0xf bank_mask:0xf bound_ctrl:1
	s_nop 1
	v_add_f32_dpp v6, v6, v6 quad_perm:[2,3,0,1] row_mask:0xf bank_mask:0xf bound_ctrl:1
	s_nop 1
	v_add_f32_dpp v6, v6, v6 row_half_mirror row_mask:0xf bank_mask:0xf bound_ctrl:1
	v_fmamk_f32 v6, v6, 0x3c800000, v250
	v_rsq_f32_e32 v6, v6
	s_nop 0
	v_pk_mul_f32 v[84:85], v[6:7], v[28:29] op_sel_hi:[0,1]
	v_pk_mul_f32 v[8:9], v[6:7], v[8:9] op_sel_hi:[0,1]
	v_pk_mul_f32 v[86:87], v[6:7], v[26:27] op_sel_hi:[0,1]
	v_pk_mul_f32 v[6:7], v[6:7], v[24:25] op_sel_hi:[0,1]
	v_pk_mul_f32 v[84:85], v[16:17], v[84:85]
	v_pk_mul_f32 v[8:9], v[18:19], v[8:9]
	v_pk_mul_f32 v[86:87], v[20:21], v[86:87]
	v_pk_mul_f32 v[88:89], v[22:23], v[6:7]
	v_cvt_pk_bf16_f32 v6, v84, v85
	v_cvt_pk_bf16_f32 v7, v8, v9
	v_cvt_pk_bf16_f32 v8, v86, v87
	v_cvt_pk_bf16_f32 v9, v88, v89
	ds_write_b128 v31, v[6:9]
	v_add_u32_e32 v31, s12, v31
	s_waitcnt vmcnt(12)
	ds_write_b16 v35, v56 offset:36992
	ds_write_b16_d16_hi v35, v56 offset:37512
	ds_write_b16 v35, v57 offset:38032
	ds_write_b16_d16_hi v35, v57 offset:38552
	ds_write_b16 v35, v58 offset:39072
	ds_write_b16_d16_hi v35, v58 offset:39592
	ds_write_b16 v35, v59 offset:40112
	ds_write_b16_d16_hi v35, v59 offset:40632
	s_waitcnt vmcnt(11)
; __device__ __forceinline__ float sum8(float s) { s += DPP_MOVF(s, 0xB1); s += DPP_MOVF(s, 0x4E); s += DPP_MOVF(s, 0x141); return s; }
; #define LAS __attribute__((address_space(3)))
; __device__ __forceinline__ void attn_phase(int wave_s, LAS unsigned char* lds, const bf16* QKV, bf16* O, const float* qg, const float* kg, const float* sinks, const float* bt) {
;     ...
;         for (int i = 0; i < 4; ++i) { int tq = tid; asm volatile("" : "+v"(tq)); const int p = tq + NTHR * i, jrow = p >> 3, ch = p & 7; const bool ok = (nb > 0) || (jrow >= 128);
;             v4u kw = (v4u){0u, 0u, 0u, 0u}, vw = (v4u){0u, 0u, 0u, 0u};
;             if (ok) { const bf16* src = QKV + (size_t)(rowbase + jrow) * NQKV + NH * HD + kvh * HD + ch * 8; kw = *(const v4u*)src; vw = *(const v4u*)(src + NKV * HD); }
;             float kf[8] = {bflo(kw.x), bfhi(kw.x), bflo(kw.y), bfhi(kw.y), bflo(kw.z), bfhi(kw.z), bflo(kw.w), bfhi(kw.w)};
;             float s = 0.f;
; #pragma unroll
;             for (int e = 0; e < 8; ++e) s += kf[e] * kf[e];
;             s = sum8(s);
;             const float rs = __builtin_amdgcn_rsqf(s * (1.0f / 64.0f) + EPS);
;             const f32x4 g0 = *(const f32x4*)(kg + ch * 8), g1 = *(const f32x4*)(kg + ch * 8 + 4);
;             v4u ko; ko.x = pk2(kf[0] * rs * g0.x, kf[1] * rs * g0.y); ko.y = pk2(kf[2] * rs * g0.z, kf[3] * rs * g0.w); ko.z = pk2(kf[4] * rs * g1.x, kf[5] * rs * g1.y); ko.w = pk2(kf[6] * rs * g1.z, kf[7] * rs * g1.w);
;             *(LAS v4u*)(Ks + jrow * KS_STRIDE + ch * 8) = ko;
;             LAS bf16* vd = Vt + (ch * 8) * VT_STRIDE + jrow;
;             vd[0 * VT_STRIDE] = (bf16)(vw.x & 0xffffu); vd[1 * VT_STRIDE] = (bf16)(vw.x >> 16); vd[2 * VT_STRIDE] = (bf16)(vw.y & 0xffffu); vd[3 * VT_STRIDE] = (bf16)(vw.y >> 16);
;             vd[4 * VT_STRIDE] = (bf16)(vw.z & 0xffffu); vd[5 * VT_STRIDE] = (bf16)(vw.z >> 16); vd[6 * VT_STRIDE] = (bf16)(vw.w & 0xffffu); vd[7 * VT_STRIDE] = (bf16)(vw.w >> 16); }
;         for (int e = tid; e < 8 * 192; e += NTHR) { const int hh = e / 192, dist = e % 192 - 32; Bs[e] = (dist >= 0 && dist < 128) ? bt[(kvh * 8 + hh) * 128 + dist] - shift * LOG2E : -1e30f; }
;         __syncthreads();
;         const int h = kvh * 8 + wid; const float sink2 = (sinks[h] - shift) * LOG2E;
	v_lshlrev_b32_e32 v28, 16, v44
	v_and_b32_e32 v29, 0xffff0000, v44
	v_lshlrev_b32_e32 v24, 16, v47
	v_and_b32_e32 v25, 0xffff0000, v47
	v_lshlrev_b32_e32 v26, 16, v46
	v_and_b32_e32 v27, 0xffff0000, v46
	v_lshlrev_b32_e32 v8, 16, v45
	v_and_b32_e32 v9, 0xffff0000, v45
	v_pk_mul_f32 v[90:91], v[28:29], v[28:29]
	v_pk_mul_f32 v[84:85], v[8:9], v[8:9]
	v_add_f32_e32 v90, v90, v91
	v_add_f32_e32 v84, v84, v90
	v_pk_mul_f32 v[86:87], v[26:27], v[26:27]
	v_add_f32_e32 v84, v85, v84
	v_add_f32_e32 v86, v86, v84
	v_pk_mul_f32 v[6:7], v[24:25], v[24:25]
	v_add_f32_e32 v86, v87, v86
	v_add_f32_e32 v6, v6, v86
	v_add_f32_e32 v6, v7, v6
	s_nop 1
	v_add_f32_dpp v6, v6, v6 quad_perm:[1,0,3,2] row_mask:0xf bank_mask:0xf bound_ctrl:1
	s_nop 1
	v_add_f32_dpp v6, v6, v6 quad_perm:[2,3,0,1] row_mask:0xf bank_mask:0xf bound_ctrl:1
	s_nop 1
	v_add_f32_dpp v6, v6, v6 row_half_mirror row_mask:0xf bank_mask:0xf bound_ctrl:1
	v_fmamk_f32 v6, v6, 0x3c800000, v250
	v_rsq_f32_e32 v6, v6
	s_nop 0
	v_pk_mul_f32 v[84:85], v[6:7], v[28:29] op_sel_hi:[0,1]
	v_pk_mul_f32 v[8:9], v[6:7], v[8:9] op_sel_hi:[0,1]
	v_pk_mul_f32 v[86:87], v[6:7], v[26:27] op_sel_hi:[0,1]
	v_pk_mul_f32 v[6:7], v[6:7], v[24:25] op_sel_hi:[0,1]
	v_pk_mul_f32 v[84:85], v[16:17], v[84:85]
	v_pk_mul_f32 v[8:9], v[18:19], v[8:9]
	v_pk_mul_f32 v[86:87], v[20:21], v[86:87]
	v_pk_mul_f32 v[88:89], v[22:23], v[6:7]
	v_cvt_pk_bf16_f32 v6, v84, v85
	v_cvt_pk_bf16_f32 v7, v8, v9
	v_cvt_pk_bf16_f32 v8, v86, v87
	v_cvt_pk_bf16_f32 v9, v88, v89
	ds_write_b128 v31, v[6:9]
	v_add_u32_e32 v31, s12, v31
	s_waitcnt vmcnt(10)
	ds_write_b16 v35, v60 offset:37120
	ds_write_b16_d16_hi v35, v60 offset:37640
	ds_write_b16 v35, v61 offset:38160
	ds_write_b16_d16_hi v35, v61 offset:38680
	ds_write_b16 v35, v62 offset:39200
	ds_write_b16_d16_hi v35, v62 offset:39720
	ds_write_b16 v35, v63 offset:40240
	ds_write_b16_d16_hi v35, v63 offset:40760
	s_waitcnt vmcnt(9)
	v_lshlrev_b32_e32 v28, 16, v48
	v_and_b32_e32 v29, 0xffff0000, v48
	v_lshlrev_b32_e32 v24, 16, v51
	v_and_b32_e32 v25, 0xffff0000, v51
	v_lshlrev_b32_e32 v26, 16, v50
	v_and_b32_e32 v27, 0xffff0000, v50
	v_lshlrev_b32_e32 v8, 16, v49
	v_and_b32_e32 v9, 0xffff0000, v49
	v_pk_mul_f32 v[90:91], v[28:29], v[28:29]
	v_pk_mul_f32 v[84:85], v[8:9], v[8:9]
	v_add_f32_e32 v90, v90, v91
	v_add_f32_e32 v84, v84, v90
	v_pk_mul_f32 v[86:87], v[26:27], v[26:27]
	v_add_f32_e32 v84, v85, v84
	v_add_f32_e32 v86, v86, v84
	v_pk_mul_f32 v[6:7], v[24:25], v[24:25]
	v_add_f32_e32 v86, v87, v86
	v_add_f32_e32 v6, v6, v86
	v_add_f32_e32 v6, v7, v6
	s_nop 1
	v_add_f32_dpp v6, v6, v6 quad_perm:[1,0,3,2] row_mask:0xf bank_mask:0xf bound_ctrl:1
	s_nop 1
	v_add_f32_dpp v6, v6, v6 quad_perm:[2,3,0,1] row_mask:0xf bank_mask:0xf bound_ctrl:1
	s_nop 1
	v_add_f32_dpp v6, v6, v6 row_half_mirror row_mask:0xf bank_mask:0xf bound_ctrl:1
	v_fmamk_f32 v6, v6, 0x3c800000, v250
	v_rsq_f32_e32 v6, v6
	s_nop 0
	v_pk_mul_f32 v[84:85], v[6:7], v[28:29] op_sel_hi:[0,1]
	v_pk_mul_f32 v[8:9], v[6:7], v[8:9] op_sel_hi:[0,1]
	v_pk_mul_f32 v[86:87], v[6:7], v[26:27] op_sel_hi:[0,1]
	v_pk_mul_f32 v[6:7], v[6:7], v[24:25] op_sel_hi:[0,1]
	v_pk_mul_f32 v[84:85], v[16:17], v[84:85]
	v_pk_mul_f32 v[8:9], v[18:19], v[8:9]
	v_pk_mul_f32 v[86:87], v[20:21], v[86:87]
	v_pk_mul_f32 v[88:89], v[22:23], v[6:7]
	v_cvt_pk_bf16_f32 v6, v84, v85
	v_cvt_pk_bf16_f32 v7, v8, v9
	v_cvt_pk_bf16_f32 v8, v86, v87
	v_cvt_pk_bf16_f32 v9, v88, v89
	ds_write_b128 v31, v[6:9]
	s_waitcnt vmcnt(8)
	ds_write_b16 v35, v64 offset:37248
	ds_write_b16_d16_hi v35, v64 offset:37768
	ds_write_b16 v35, v65 offset:38288
	ds_write_b16_d16_hi v35, v65 offset:38808
	ds_write_b16 v35, v66 offset:39328
	ds_write_b16_d16_hi v35, v66 offset:39848
	ds_write_b16 v35, v67 offset:40368
	ds_write_b16_d16_hi v35, v67 offset:40888
	s_and_saveexec_b64 s[12:13], s[14:15]
	s_cbranch_execz .LBB0_497
	v_mov_b32_e32 v95, 0xf149f2ca
	s_waitcnt vmcnt(5)
	v_sub_f32_e32 v92, v92, v144
	v_sub_f32_e32 v93, v93, v144
	v_sub_f32_e32 v94, v94, v144
	v_cndmask_b32_e64 v92, v95, v92, s[40:41]
	v_cndmask_b32_e64 v93, v95, v93, s[84:85]
	v_cndmask_b32_e64 v94, v95, v94, s[90:91]
	ds_write_b32 v112, v92
	ds_write_b32 v112, v93 offset:2048
	ds_write_b32 v112, v94 offset:4096
.LBB0_497:
	s_or_b64 exec, exec, s[12:13]
	s_waitcnt lgkmcnt(0)
	s_barrier
	s_add_u32 s8, s37, s8
	s_addc_u32 s9, 0, s9
	s_lshl_b64 s[6:7], s[6:7], 25
	v_mov_b64_e32 v[2:3], s[2:3]
	v_lshl_add_u64 v[4:5], s[8:9], 0, v[128:129]
	s_or_b32 s6, s6, s36
	v_mad_u64_u32 v[2:3], s[8:9], v4, s70, v[2:3]
	s_add_u32 s2, s6, s2
	v_mad_i32_i24 v3, v5, s70, v3
	s_addc_u32 s3, s7, s3
	v_lshl_add_u64 v[138:139], v[132:133], 0, v[2:3]
	v_lshl_add_u64 v[140:141], v[134:135], 0, s[2:3]
	s_mov_b32 s36, 0
	s_mov_b64 s[90:91], 0
	v_mov_b32_e32 v156, v151
	v_mov_b32_e32 v157, v150
	s_waitcnt vmcnt(4)
	v_sub_f32_e32 v1, v1, v143
	v_mul_f32_e32 v1, 0x3fb8aa3b, v1
	v_exp_f32_e32 v137, v1
	s_waitcnt vmcnt(0)
	s_and_b64 vcc, exec, s[88:89]
	s_cbranch_vccnz .Lfa_top
	s_branch .LBB0_499
